# adds: RSTD pre-pass of the GEMM phases loads its 8 partial sums together instead of as a dependent chain (same summation order)
# baseline (speedup 1.0000x reference)
;     __device__ __forceinline__ bool next(int i, Unit& u) const {
;         if (i + i0 >= i1) return false;
;         const long L = (long)(i + i0) * G + c; if (L >= nwg) return false;
;         int wgid = (int)L; { const int q = nwg / NXCD, r = nwg % NXCD, xcd = wgid % NXCD, off = wgid / NXCD; wgid = (xcd < r ? xcd * (q + 1) : r * (q + 1) + (xcd - r) * q) + off; }
;         const int nig = WGM * nN, gid = wgid / nig, fm = gid * WGM, gsz = (nM - fm) < WGM ? (nM - fm) : WGM;
;         u.pm = fm + ((wgid % nig) % gsz); u.pn = (wgid % nig) / gsz;
;         u.aoff = (long)u.pm * a_pm + (long)(u.pn >> a_sh) * a_pn; u.boff = (long)(u.pm >> b_sh) * b_pm + (long)u.pn * b_pn;
; template <class Epi, bool ALIGN_EPI = true>
; __device__ __forceinline__ void gemm_phase(LAS unsigned char* lds, const Gemm g, const Sched& S, const Epi& E) {
;     ...
;         for (int k = 0; k < RSTD_UNITS * 256 / 512; ++k) { const int idx = tid + 512 * k; Unit uu;
;             if (S.next(idx >> 8, uu)) { const float* sp = E.SS + uu.pm * BM + (idx & 255); float ssum = 0.f;
; #pragma unroll
;                 for (int j = 0; j < 8; ++j) ssum += sp[(size_t)j * MROWS];
;                 T[idx] = __builtin_amdgcn_rsqf(ssum * (1.0f / DM) + EPS); } }
.LBB0_484:
	s_add_u32 s26, s54, s26
	s_addc_u32 s27, s55, s27
	v_lshlrev_b32_sdwa v2, v214, v12 dst_sel:DWORD dst_unused:UNUSED_PAD src0_sel:DWORD src1_sel:BYTE_0
	s_waitcnt lgkmcnt(0)
	v_lshl_add_u64 v[4:5], s[26:27], 0, v[2:3]
	v_ashrrev_i32_e32 v2, 8, v12
	v_mov_b64_e32 v[6:7], s[2:3]
	v_mad_i64_i32 v[6:7], s[26:27], v2, s12, v[6:7]
	s_mov_b64 s[26:27], 0x480
	v_cmp_gt_i32_e32 vcc, 4, v2
	v_cmp_gt_i64_e64 s[40:41], s[26:27], v[6:7]
	s_and_b64 s[30:31], vcc, s[40:41]
	s_and_saveexec_b64 s[26:27], s[30:31]
	s_cbranch_execz .LBB0_486
	v_ashrrev_i32_e32 v2, 31, v6
	v_lshrrev_b32_e32 v2, 29, v2
	v_add_u32_e32 v2, v6, v2
	v_ashrrev_i32_e32 v7, 3, v2
	v_and_b32_e32 v2, -8, v2
	v_sub_u32_e32 v2, v6, v2
	v_cmp_gt_i32_e32 vcc, 0, v2
	s_mov_b32 s10, 0x38e38e39
	s_nop 0
	v_cndmask_b32_e32 v6, v215, v216, vcc
	v_mul_lo_u32 v2, v2, v6
	v_add_u32_e32 v2, v2, v7
	v_mul_hi_i32 v6, v2, s10
	v_lshrrev_b32_e32 v7, 31, v6
	v_ashrrev_i32_e32 v6, 6, v6
	v_add_u32_e32 v6, v6, v7
	v_lshlrev_b32_e32 v7, 3, v6
	v_mul_i32_i24_e32 v6, 0x120, v6
	v_sub_u32_e32 v8, 32, v7
	v_sub_u32_e32 v2, v2, v6
	v_min_i32_e32 v8, 8, v8
	v_sub_u32_e32 v9, 0, v2
	v_ashrrev_i32_e32 v6, 31, v2
	v_max_i32_e32 v2, v2, v9
	v_sub_u32_e32 v9, 0, v8
	v_max_i32_e32 v8, v8, v9
	v_cvt_f32_u32_e32 v9, v8
	v_sub_u32_e32 v10, 0, v8
	s_mov_b32 s10, 0x10000
	v_rcp_iflag_f32_e32 v9, v9
	s_nop 0
	v_mul_f32_e32 v9, 0x4f7ffffe, v9
	v_cvt_u32_f32_e32 v9, v9
	v_mul_lo_u32 v10, v10, v9
	v_mul_hi_u32 v10, v9, v10
	v_add_u32_e32 v9, v9, v10
	v_mul_hi_u32 v9, v2, v9
	v_mul_lo_u32 v9, v9, v8
	v_sub_u32_e32 v2, v2, v9
	v_cmp_ge_u32_e32 vcc, v2, v8
	v_sub_u32_e32 v9, v2, v8
	s_nop 0
	v_cndmask_b32_e32 v2, v2, v9, vcc
	v_cmp_ge_u32_e32 vcc, v2, v8
	v_sub_u32_e32 v8, v2, v8
	s_nop 0
	v_cndmask_b32_e32 v2, v2, v8, vcc
	v_xor_b32_e32 v2, v2, v6
	v_sub_u32_e32 v2, v2, v6
	v_add_lshl_u32 v6, v7, v2, 8
	v_ashrrev_i32_e32 v7, 31, v6
	v_lshl_add_u64 v[6:7], v[6:7], 2, v[4:5]
	global_load_dword v100, v[6:7], off
	v_add_co_u32_e32 v110, vcc, 0x8000, v6
	s_nop 1
	v_addc_co_u32_e32 v111, vcc, 0, v7, vcc
	global_load_dword v101, v[110:111], off
	v_add_co_u32_e32 v110, vcc, 0x10000, v6
	s_nop 1
	v_addc_co_u32_e32 v111, vcc, 0, v7, vcc
	global_load_dword v102, v[110:111], off
	v_add_co_u32_e32 v110, vcc, 0x18000, v6
	s_nop 1
	v_addc_co_u32_e32 v111, vcc, 0, v7, vcc
	global_load_dword v103, v[110:111], off
	v_add_co_u32_e32 v110, vcc, 0x20000, v6
	s_nop 1
	v_addc_co_u32_e32 v111, vcc, 0, v7, vcc
	global_load_dword v104, v[110:111], off
	v_add_co_u32_e32 v110, vcc, 0x28000, v6
	s_nop 1
	v_addc_co_u32_e32 v111, vcc, 0, v7, vcc
	global_load_dword v105, v[110:111], off
	v_add_co_u32_e32 v110, vcc, 0x30000, v6
	s_nop 1
	v_addc_co_u32_e32 v111, vcc, 0, v7, vcc
	global_load_dword v106, v[110:111], off
	v_add_co_u32_e32 v110, vcc, 0x38000, v6
	s_nop 1
	v_addc_co_u32_e32 v111, vcc, 0, v7, vcc
	global_load_dword v107, v[110:111], off
	s_mov_b32 s10, 0x28000
	s_waitcnt vmcnt(0)
	v_add_f32_e32 v2, 0, v100
	v_add_f32_e32 v2, v2, v101
	v_add_f32_e32 v2, v2, v102
	v_add_f32_e32 v2, v2, v103
	v_add_f32_e32 v2, v2, v104
	v_add_f32_e32 v2, v2, v105
	v_add_f32_e32 v2, v2, v106
	v_add_f32_e32 v2, v2, v107
	v_fmamk_f32 v2, v2, 0x3a000000, v212
	v_rsq_f32_e32 v2, v2
	v_lshl_add_u32 v6, v12, 2, 0
	v_add_u32_e32 v6, 0x20000, v6
	ds_write_b32 v6, v2
;     __device__ __forceinline__ bool next(int i, Unit& u) const {
;         if (i + i0 >= i1) return false;
;         const long L = (long)(i + i0) * G + c; if (L >= nwg) return false;
;         int wgid = (int)L; { const int q = nwg / NXCD, r = nwg % NXCD, xcd = wgid % NXCD, off = wgid / NXCD; wgid = (xcd < r ? xcd * (q + 1) : r * (q + 1) + (xcd - r) * q) + off; }
;         const int nig = WGM * nN, gid = wgid / nig, fm = gid * WGM, gsz = (nM - fm) < WGM ? (nM - fm) : WGM;
;         u.pm = fm + ((wgid % nig) % gsz); u.pn = (wgid % nig) / gsz;
;         u.aoff = (long)u.pm * a_pm + (long)(u.pn >> a_sh) * a_pn; u.boff = (long)(u.pm >> b_sh) * b_pm + (long)u.pn * b_pn;
; template <class Epi, bool ALIGN_EPI = true>
; __device__ __forceinline__ void gemm_phase(LAS unsigned char* lds, const Gemm g, const Sched& S, const Epi& E) {
;     ...
;         for (int k = 0; k < RSTD_UNITS * 256 / 512; ++k) { const int idx = tid + 512 * k; Unit uu;
;             if (S.next(idx >> 8, uu)) { const float* sp = E.SS + uu.pm * BM + (idx & 255); float ssum = 0.f;
; #pragma unroll
;                 for (int j = 0; j < 8; ++j) ssum += sp[(size_t)j * MROWS];
;                 T[idx] = __builtin_amdgcn_rsqf(ssum * (1.0f / DM) + EPS); } }
.LBB0_486:
	s_or_b64 exec, exec, s[26:27]
	v_add_u32_e32 v2, 0x200, v12
	v_ashrrev_i32_e32 v8, 8, v2
	v_mov_b64_e32 v[6:7], s[2:3]
	v_mad_i64_i32 v[6:7], s[26:27], v8, s12, v[6:7]
	s_mov_b64 s[26:27], 0x480
	v_cmp_gt_i32_e32 vcc, 4, v8
	v_cmp_gt_i64_e64 s[40:41], s[26:27], v[6:7]
	s_and_b64 s[30:31], vcc, s[40:41]
	s_and_saveexec_b64 s[26:27], s[30:31]
	v_readlane_b32 s38, v242, 25
	v_readlane_b32 s39, v242, 26
	s_cbranch_execz .LBB0_488
	v_ashrrev_i32_e32 v7, 31, v6
	v_lshrrev_b32_e32 v7, 29, v7
	v_add_u32_e32 v7, v6, v7
	v_ashrrev_i32_e32 v8, 3, v7
	v_and_b32_e32 v7, -8, v7
	v_sub_u32_e32 v6, v6, v7
	v_cmp_gt_i32_e32 vcc, 0, v6
	s_mov_b32 s10, 0x38e38e39
	v_lshl_add_u32 v2, v2, 2, 0
	v_cndmask_b32_e32 v7, v215, v216, vcc
	v_mul_lo_u32 v6, v6, v7
	v_add_u32_e32 v6, v6, v8
	v_mul_hi_i32 v7, v6, s10
	v_lshrrev_b32_e32 v8, 31, v7
	v_ashrrev_i32_e32 v7, 6, v7
	v_add_u32_e32 v7, v7, v8
	v_lshlrev_b32_e32 v8, 3, v7
	v_mul_i32_i24_e32 v7, 0x120, v7
	v_sub_u32_e32 v9, 32, v8
	v_sub_u32_e32 v6, v6, v7
	v_min_i32_e32 v9, 8, v9
	v_sub_u32_e32 v10, 0, v6
	v_ashrrev_i32_e32 v7, 31, v6
	v_max_i32_e32 v6, v6, v10
	v_sub_u32_e32 v10, 0, v9
	v_max_i32_e32 v9, v9, v10
	v_cvt_f32_u32_e32 v10, v9
	v_sub_u32_e32 v11, 0, v9
	s_mov_b32 s10, 0x10000
	v_add_u32_e32 v2, 0x20000, v2
	v_rcp_iflag_f32_e32 v10, v10
	s_nop 0
	v_mul_f32_e32 v10, 0x4f7ffffe, v10
	v_cvt_u32_f32_e32 v10, v10
	v_mul_lo_u32 v11, v11, v10
	v_mul_hi_u32 v11, v10, v11
	v_add_u32_e32 v10, v10, v11
	v_mul_hi_u32 v10, v6, v10
	v_mul_lo_u32 v10, v10, v9
	v_sub_u32_e32 v6, v6, v10
	v_cmp_ge_u32_e32 vcc, v6, v9
	v_sub_u32_e32 v10, v6, v9
	s_nop 0
	v_cndmask_b32_e32 v6, v6, v10, vcc
	v_cmp_ge_u32_e32 vcc, v6, v9
	v_sub_u32_e32 v9, v6, v9
	s_nop 0
	v_cndmask_b32_e32 v6, v6, v9, vcc
	v_xor_b32_e32 v6, v6, v7
	v_sub_u32_e32 v6, v6, v7
	v_add_lshl_u32 v6, v8, v6, 8
	v_ashrrev_i32_e32 v7, 31, v6
	v_lshl_add_u64 v[6:7], v[6:7], 2, v[4:5]
	global_load_dword v100, v[6:7], off
	v_add_co_u32_e32 v110, vcc, 0x8000, v6
	s_nop 1
	v_addc_co_u32_e32 v111, vcc, 0, v7, vcc
	global_load_dword v101, v[110:111], off
	v_add_co_u32_e32 v110, vcc, 0x10000, v6
	s_nop 1
	v_addc_co_u32_e32 v111, vcc, 0, v7, vcc
	global_load_dword v102, v[110:111], off
	v_add_co_u32_e32 v110, vcc, 0x18000, v6
	s_nop 1
	v_addc_co_u32_e32 v111, vcc, 0, v7, vcc
	global_load_dword v103, v[110:111], off
	v_add_co_u32_e32 v110, vcc, 0x20000, v6
	s_nop 1
	v_addc_co_u32_e32 v111, vcc, 0, v7, vcc
	global_load_dword v104, v[110:111], off
	v_add_co_u32_e32 v110, vcc, 0x28000, v6
	s_nop 1
	v_addc_co_u32_e32 v111, vcc, 0, v7, vcc
	global_load_dword v105, v[110:111], off
	v_add_co_u32_e32 v110, vcc, 0x30000, v6
	s_nop 1
	v_addc_co_u32_e32 v111, vcc, 0, v7, vcc
	global_load_dword v106, v[110:111], off
	v_add_co_u32_e32 v110, vcc, 0x38000, v6
	s_nop 1
	v_addc_co_u32_e32 v111, vcc, 0, v7, vcc
	global_load_dword v107, v[110:111], off
	s_mov_b32 s10, 0x28000
	s_waitcnt vmcnt(0)
	v_add_f32_e32 v6, 0, v100
	v_add_f32_e32 v6, v6, v101
	v_add_f32_e32 v6, v6, v102
	v_add_f32_e32 v6, v6, v103
	v_add_f32_e32 v6, v6, v104
	v_add_f32_e32 v6, v6, v105
	v_add_f32_e32 v6, v6, v106
	v_add_f32_e32 v6, v6, v107
	v_fmamk_f32 v6, v6, 0x3a000000, v212
	v_rsq_f32_e32 v6, v6
	ds_write_b32 v2, v6
.LBB0_488:
	s_or_b64 exec, exec, s[26:27]
	v_add_u32_e32 v2, 0x400, v12
	v_ashrrev_i32_e32 v8, 8, v2
	v_mov_b64_e32 v[6:7], s[2:3]
	v_mad_i64_i32 v[6:7], s[26:27], v8, s12, v[6:7]
	s_mov_b64 s[26:27], 0x480
	v_cmp_gt_i32_e32 vcc, 4, v8
	v_cmp_gt_i64_e64 s[40:41], s[26:27], v[6:7]
	s_and_b64 s[30:31], vcc, s[40:41]
	s_and_saveexec_b64 s[26:27], s[30:31]
	s_cbranch_execz .LBB0_490
	v_ashrrev_i32_e32 v7, 31, v6
	v_lshrrev_b32_e32 v7, 29, v7
	v_add_u32_e32 v7, v6, v7
	v_ashrrev_i32_e32 v8, 3, v7
	v_and_b32_e32 v7, -8, v7
	v_sub_u32_e32 v6, v6, v7
	v_cmp_gt_i32_e32 vcc, 0, v6
	s_mov_b32 s10, 0x38e38e39
	v_lshl_add_u32 v2, v2, 2, 0
	v_cndmask_b32_e32 v7, v215, v216, vcc
	v_mul_lo_u32 v6, v6, v7
	v_add_u32_e32 v6, v6, v8
	v_mul_hi_i32 v7, v6, s10
	v_lshrrev_b32_e32 v8, 31, v7
	v_ashrrev_i32_e32 v7, 6, v7
	v_add_u32_e32 v7, v7, v8
	v_lshlrev_b32_e32 v8, 3, v7
	v_mul_i32_i24_e32 v7, 0x120, v7
	v_sub_u32_e32 v9, 32, v8
	v_sub_u32_e32 v6, v6, v7
	v_min_i32_e32 v9, 8, v9
	v_sub_u32_e32 v10, 0, v6
	v_ashrrev_i32_e32 v7, 31, v6
	v_max_i32_e32 v6, v6, v10
	v_sub_u32_e32 v10, 0, v9
	v_max_i32_e32 v9, v9, v10
	v_cvt_f32_u32_e32 v10, v9
	v_sub_u32_e32 v11, 0, v9
	s_mov_b32 s10, 0x10000
	v_add_u32_e32 v2, 0x20000, v2
	v_rcp_iflag_f32_e32 v10, v10
	s_nop 0
	v_mul_f32_e32 v10, 0x4f7ffffe, v10
	v_cvt_u32_f32_e32 v10, v10
	v_mul_lo_u32 v11, v11, v10
	v_mul_hi_u32 v11, v10, v11
	v_add_u32_e32 v10, v10, v11
	v_mul_hi_u32 v10, v6, v10
	v_mul_lo_u32 v10, v10, v9
	v_sub_u32_e32 v6, v6, v10
	v_cmp_ge_u32_e32 vcc, v6, v9
	v_sub_u32_e32 v10, v6, v9
	s_nop 0
	v_cndmask_b32_e32 v6, v6, v10, vcc
	v_cmp_ge_u32_e32 vcc, v6, v9
	v_sub_u32_e32 v9, v6, v9
	s_nop 0
	v_cndmask_b32_e32 v6, v6, v9, vcc
	v_xor_b32_e32 v6, v6, v7
	v_sub_u32_e32 v6, v6, v7
	v_add_lshl_u32 v6, v8, v6, 8
	v_ashrrev_i32_e32 v7, 31, v6
	v_lshl_add_u64 v[4:5], v[6:7], 2, v[4:5]
	global_load_dword v100, v[4:5], off
	v_add_co_u32_e32 v110, vcc, 0x8000, v4
	s_nop 1
	v_addc_co_u32_e32 v111, vcc, 0, v5, vcc
	global_load_dword v101, v[110:111], off
	v_add_co_u32_e32 v110, vcc, 0x10000, v4
	s_nop 1
	v_addc_co_u32_e32 v111, vcc, 0, v5, vcc
	global_load_dword v102, v[110:111], off
	v_add_co_u32_e32 v110, vcc, 0x18000, v4
	s_nop 1
	v_addc_co_u32_e32 v111, vcc, 0, v5, vcc
	global_load_dword v103, v[110:111], off
	v_add_co_u32_e32 v110, vcc, 0x20000, v4
	s_nop 1
	v_addc_co_u32_e32 v111, vcc, 0, v5, vcc
	global_load_dword v104, v[110:111], off
	v_add_co_u32_e32 v110, vcc, 0x28000, v4
	s_nop 1
	v_addc_co_u32_e32 v111, vcc, 0, v5, vcc
	global_load_dword v105, v[110:111], off
	v_add_co_u32_e32 v110, vcc, 0x30000, v4
	s_nop 1
	v_addc_co_u32_e32 v111, vcc, 0, v5, vcc
	global_load_dword v106, v[110:111], off
	v_add_co_u32_e32 v110, vcc, 0x38000, v4
	s_nop 1
	v_addc_co_u32_e32 v111, vcc, 0, v5, vcc
	global_load_dword v107, v[110:111], off
	s_mov_b32 s10, 0x28000
	s_waitcnt vmcnt(0)
	v_add_f32_e32 v4, 0, v100
	v_add_f32_e32 v4, v4, v101
	v_add_f32_e32 v4, v4, v102
	v_add_f32_e32 v4, v4, v103
	v_add_f32_e32 v4, v4, v104
	v_add_f32_e32 v4, v4, v105
	v_add_f32_e32 v4, v4, v106
	v_add_f32_e32 v4, v4, v107
	v_fmamk_f32 v4, v4, 0x3a000000, v212
	v_rsq_f32_e32 v4, v4
	ds_write_b32 v2, v4

;     __device__ __forceinline__ bool next(int i, Unit& u) const {
;         if (i + i0 >= i1) return false;
;         const long L = (long)(i + i0) * G + c; if (L >= nwg) return false;
;         int wgid = (int)L; { const int q = nwg / NXCD, r = nwg % NXCD, xcd = wgid % NXCD, off = wgid / NXCD; wgid = (xcd < r ? xcd * (q + 1) : r * (q + 1) + (xcd - r) * q) + off; }
;         const int nig = WGM * nN, gid = wgid / nig, fm = gid * WGM, gsz = (nM - fm) < WGM ? (nM - fm) : WGM;
;         u.pm = fm + ((wgid % nig) % gsz); u.pn = (wgid % nig) / gsz;
;         u.aoff = (long)u.pm * a_pm + (long)(u.pn >> a_sh) * a_pn; u.boff = (long)(u.pm >> b_sh) * b_pm + (long)u.pn * b_pn;
; template <class Epi, bool ALIGN_EPI = true>
; __device__ __forceinline__ void gemm_phase(LAS unsigned char* lds, const Gemm g, const Sched& S, const Epi& E) {
;     ...
;         for (int k = 0; k < RSTD_UNITS * 256 / 512; ++k) { const int idx = tid + 512 * k; Unit uu;
;             if (S.next(idx >> 8, uu)) { const float* sp = E.SS + uu.pm * BM + (idx & 255); float ssum = 0.f;
; #pragma unroll
;                 for (int j = 0; j < 8; ++j) ssum += sp[(size_t)j * MROWS];
;                 T[idx] = __builtin_amdgcn_rsqf(ssum * (1.0f / DM) + EPS); } }
.LBB0_937:
	s_and_b64 vcc, exec, s[40:41]
	s_cbranch_vccnz .LBB0_991
	v_readlane_b32 s36, v246, 42
	v_readlane_b32 s38, v246, 44
	v_readlane_b32 s39, v246, 45
	s_add_u32 s26, s38, s26
	s_addc_u32 s27, s39, s27
	v_lshlrev_b32_sdwa v2, v214, v12 dst_sel:DWORD dst_unused:UNUSED_PAD src0_sel:DWORD src1_sel:BYTE_0
	s_waitcnt lgkmcnt(0)
	v_lshl_add_u64 v[4:5], s[26:27], 0, v[2:3]
	v_ashrrev_i32_e32 v2, 8, v12
	s_mov_b32 s10, 0xffffc
	v_cmp_gt_i32_e32 vcc, s10, v2
	v_add_u32_e32 v2, 4, v2
	v_mov_b64_e32 v[6:7], s[2:3]
	v_mad_i64_i32 v[6:7], s[26:27], v2, s12, v[6:7]
	s_mov_b64 s[26:27], 0x480
	s_nop 0
	v_cmp_gt_i64_e64 s[40:41], s[26:27], v[6:7]
	s_and_b64 s[30:31], vcc, s[40:41]
	v_readlane_b32 s37, v246, 43
	s_and_saveexec_b64 s[26:27], s[30:31]
	s_cbranch_execz .LBB0_940
	v_ashrrev_i32_e32 v2, 31, v6
	v_lshrrev_b32_e32 v2, 29, v2
	v_add_u32_e32 v2, v6, v2
	v_ashrrev_i32_e32 v7, 3, v2
	v_and_b32_e32 v2, -8, v2
	v_sub_u32_e32 v2, v6, v2
	v_cmp_gt_i32_e32 vcc, 0, v2
	s_mov_b32 s10, 0x38e38e39
	s_nop 0
	v_cndmask_b32_e32 v6, v215, v216, vcc
	v_mul_lo_u32 v2, v2, v6
	v_add_u32_e32 v2, v2, v7
	v_mul_hi_i32 v6, v2, s10
	v_lshrrev_b32_e32 v7, 31, v6
	v_ashrrev_i32_e32 v6, 6, v6
	v_add_u32_e32 v6, v6, v7
	v_lshlrev_b32_e32 v7, 3, v6
	v_mul_i32_i24_e32 v6, 0x120, v6
	v_sub_u32_e32 v8, 32, v7
	v_sub_u32_e32 v2, v2, v6
	v_min_i32_e32 v8, 8, v8
	v_sub_u32_e32 v9, 0, v2
	v_ashrrev_i32_e32 v6, 31, v2
	v_max_i32_e32 v2, v2, v9
	v_sub_u32_e32 v9, 0, v8
	v_max_i32_e32 v8, v8, v9
	v_cvt_f32_u32_e32 v9, v8
	v_sub_u32_e32 v10, 0, v8
	v_rcp_iflag_f32_e32 v9, v9
	s_nop 0
	v_mul_f32_e32 v9, 0x4f7ffffe, v9
	v_cvt_u32_f32_e32 v9, v9
	v_mul_lo_u32 v10, v10, v9
	v_mul_hi_u32 v10, v9, v10
	v_add_u32_e32 v9, v9, v10
	v_mul_hi_u32 v9, v2, v9
	v_mul_lo_u32 v9, v9, v8
	v_sub_u32_e32 v2, v2, v9
	v_cmp_ge_u32_e32 vcc, v2, v8
	v_sub_u32_e32 v9, v2, v8
	s_nop 0
	v_cndmask_b32_e32 v2, v2, v9, vcc
	v_cmp_ge_u32_e32 vcc, v2, v8
	v_sub_u32_e32 v8, v2, v8
	s_nop 0
	v_cndmask_b32_e32 v2, v2, v8, vcc
	v_xor_b32_e32 v2, v2, v6
	v_sub_u32_e32 v2, v2, v6
	v_add_lshl_u32 v6, v7, v2, 8
	v_ashrrev_i32_e32 v7, 31, v6
	v_lshl_add_u64 v[6:7], v[6:7], 2, v[4:5]
	global_load_dword v100, v[6:7], off
	v_add_co_u32_e32 v110, vcc, 0x8000, v6
	s_nop 1
	v_addc_co_u32_e32 v111, vcc, 0, v7, vcc
	global_load_dword v101, v[110:111], off
	v_add_co_u32_e32 v110, vcc, 0x10000, v6
	s_nop 1
	v_addc_co_u32_e32 v111, vcc, 0, v7, vcc
	global_load_dword v102, v[110:111], off
	v_add_co_u32_e32 v110, vcc, 0x18000, v6
	s_nop 1
	v_addc_co_u32_e32 v111, vcc, 0, v7, vcc
	global_load_dword v103, v[110:111], off
	v_add_co_u32_e32 v110, vcc, 0x20000, v6
	s_nop 1
	v_addc_co_u32_e32 v111, vcc, 0, v7, vcc
	global_load_dword v104, v[110:111], off
	v_add_co_u32_e32 v110, vcc, 0x28000, v6
	s_nop 1
	v_addc_co_u32_e32 v111, vcc, 0, v7, vcc
	global_load_dword v105, v[110:111], off
	v_add_co_u32_e32 v110, vcc, 0x30000, v6
	s_nop 1
	v_addc_co_u32_e32 v111, vcc, 0, v7, vcc
	global_load_dword v106, v[110:111], off
	v_add_co_u32_e32 v110, vcc, 0x38000, v6
	s_nop 1
	v_addc_co_u32_e32 v111, vcc, 0, v7, vcc
	global_load_dword v107, v[110:111], off
	s_waitcnt vmcnt(0)
	v_add_f32_e32 v2, 0, v100
	v_add_f32_e32 v2, v2, v101
	v_add_f32_e32 v2, v2, v102
	v_add_f32_e32 v2, v2, v103
	v_add_f32_e32 v2, v2, v104
	v_add_f32_e32 v2, v2, v105
	v_add_f32_e32 v2, v2, v106
	v_add_f32_e32 v2, v2, v107
	v_fmamk_f32 v2, v2, 0x3a000000, v212
	v_rsq_f32_e32 v2, v2
	v_lshl_add_u32 v6, v12, 2, 0
	v_add_u32_e32 v6, 0x20000, v6
	ds_write_b32 v6, v2
;     __device__ __forceinline__ bool next(int i, Unit& u) const {
;         if (i + i0 >= i1) return false;
;         const long L = (long)(i + i0) * G + c; if (L >= nwg) return false;
;         int wgid = (int)L; { const int q = nwg / NXCD, r = nwg % NXCD, xcd = wgid % NXCD, off = wgid / NXCD; wgid = (xcd < r ? xcd * (q + 1) : r * (q + 1) + (xcd - r) * q) + off; }
;         const int nig = WGM * nN, gid = wgid / nig, fm = gid * WGM, gsz = (nM - fm) < WGM ? (nM - fm) : WGM;
;         u.pm = fm + ((wgid % nig) % gsz); u.pn = (wgid % nig) / gsz;
;         u.aoff = (long)u.pm * a_pm + (long)(u.pn >> a_sh) * a_pn; u.boff = (long)(u.pm >> b_sh) * b_pm + (long)u.pn * b_pn;
; template <class Epi, bool ALIGN_EPI = true>
; __device__ __forceinline__ void gemm_phase(LAS unsigned char* lds, const Gemm g, const Sched& S, const Epi& E) {
;     ...
;         for (int k = 0; k < RSTD_UNITS * 256 / 512; ++k) { const int idx = tid + 512 * k; Unit uu;
;             if (S.next(idx >> 8, uu)) { const float* sp = E.SS + uu.pm * BM + (idx & 255); float ssum = 0.f;
; #pragma unroll
;                 for (int j = 0; j < 8; ++j) ssum += sp[(size_t)j * MROWS];
;                 T[idx] = __builtin_amdgcn_rsqf(ssum * (1.0f / DM) + EPS); } }
.LBB0_940:
	s_or_b64 exec, exec, s[26:27]
	v_add_u32_e32 v2, 0x200, v12
	v_ashrrev_i32_e32 v6, 8, v2
	s_mov_b32 s10, 0xffffc
	v_cmp_gt_i32_e32 vcc, s10, v6
	v_add_u32_e32 v8, 4, v6
	v_mov_b64_e32 v[6:7], s[2:3]
	v_mad_i64_i32 v[6:7], s[26:27], v8, s12, v[6:7]
	s_mov_b64 s[26:27], 0x480
	s_nop 0
	v_cmp_gt_i64_e64 s[40:41], s[26:27], v[6:7]
	s_and_b64 s[30:31], vcc, s[40:41]
	s_and_saveexec_b64 s[26:27], s[30:31]
	s_cbranch_execz .LBB0_942
	v_ashrrev_i32_e32 v7, 31, v6
	v_lshrrev_b32_e32 v7, 29, v7
	v_add_u32_e32 v7, v6, v7
	v_ashrrev_i32_e32 v8, 3, v7
	v_and_b32_e32 v7, -8, v7
	v_sub_u32_e32 v6, v6, v7
	v_cmp_gt_i32_e32 vcc, 0, v6
	s_mov_b32 s10, 0x38e38e39
	v_lshl_add_u32 v2, v2, 2, 0
	v_cndmask_b32_e32 v7, v215, v216, vcc
	v_mul_lo_u32 v6, v6, v7
	v_add_u32_e32 v6, v6, v8
	v_mul_hi_i32 v7, v6, s10
	v_lshrrev_b32_e32 v8, 31, v7
	v_ashrrev_i32_e32 v7, 6, v7
	v_add_u32_e32 v7, v7, v8
	v_lshlrev_b32_e32 v8, 3, v7
	v_mul_i32_i24_e32 v7, 0x120, v7
	v_sub_u32_e32 v9, 32, v8
	v_sub_u32_e32 v6, v6, v7
	v_min_i32_e32 v9, 8, v9
	v_sub_u32_e32 v10, 0, v6
	v_ashrrev_i32_e32 v7, 31, v6
	v_max_i32_e32 v6, v6, v10
	v_sub_u32_e32 v10, 0, v9
	v_max_i32_e32 v9, v9, v10
	v_cvt_f32_u32_e32 v10, v9
	v_sub_u32_e32 v11, 0, v9
	v_add_u32_e32 v2, 0x20000, v2
	v_rcp_iflag_f32_e32 v10, v10
	s_nop 0
	v_mul_f32_e32 v10, 0x4f7ffffe, v10
	v_cvt_u32_f32_e32 v10, v10
	v_mul_lo_u32 v11, v11, v10
	v_mul_hi_u32 v11, v10, v11
	v_add_u32_e32 v10, v10, v11
	v_mul_hi_u32 v10, v6, v10
	v_mul_lo_u32 v10, v10, v9
	v_sub_u32_e32 v6, v6, v10
	v_cmp_ge_u32_e32 vcc, v6, v9
	v_sub_u32_e32 v10, v6, v9
	s_nop 0
	v_cndmask_b32_e32 v6, v6, v10, vcc
	v_cmp_ge_u32_e32 vcc, v6, v9
	v_sub_u32_e32 v9, v6, v9
	s_nop 0
	v_cndmask_b32_e32 v6, v6, v9, vcc
	v_xor_b32_e32 v6, v6, v7
	v_sub_u32_e32 v6, v6, v7
	v_add_lshl_u32 v6, v8, v6, 8
	v_ashrrev_i32_e32 v7, 31, v6
	v_lshl_add_u64 v[6:7], v[6:7], 2, v[4:5]
	global_load_dword v100, v[6:7], off
	v_add_co_u32_e32 v110, vcc, 0x8000, v6
	s_nop 1
	v_addc_co_u32_e32 v111, vcc, 0, v7, vcc
	global_load_dword v101, v[110:111], off
	v_add_co_u32_e32 v110, vcc, 0x10000, v6
	s_nop 1
	v_addc_co_u32_e32 v111, vcc, 0, v7, vcc
	global_load_dword v102, v[110:111], off
	v_add_co_u32_e32 v110, vcc, 0x18000, v6
	s_nop 1
	v_addc_co_u32_e32 v111, vcc, 0, v7, vcc
	global_load_dword v103, v[110:111], off
	v_add_co_u32_e32 v110, vcc, 0x20000, v6
	s_nop 1
	v_addc_co_u32_e32 v111, vcc, 0, v7, vcc
	global_load_dword v104, v[110:111], off
	v_add_co_u32_e32 v110, vcc, 0x28000, v6
	s_nop 1
	v_addc_co_u32_e32 v111, vcc, 0, v7, vcc
	global_load_dword v105, v[110:111], off
	v_add_co_u32_e32 v110, vcc, 0x30000, v6
	s_nop 1
	v_addc_co_u32_e32 v111, vcc, 0, v7, vcc
	global_load_dword v106, v[110:111], off
	v_add_co_u32_e32 v110, vcc, 0x38000, v6
	s_nop 1
	v_addc_co_u32_e32 v111, vcc, 0, v7, vcc
	global_load_dword v107, v[110:111], off
	s_waitcnt vmcnt(0)
	v_add_f32_e32 v6, 0, v100
	v_add_f32_e32 v6, v6, v101
	v_add_f32_e32 v6, v6, v102
	v_add_f32_e32 v6, v6, v103
	v_add_f32_e32 v6, v6, v104
	v_add_f32_e32 v6, v6, v105
	v_add_f32_e32 v6, v6, v106
	v_add_f32_e32 v6, v6, v107
	v_fmamk_f32 v6, v6, 0x3a000000, v212
	v_rsq_f32_e32 v6, v6
	ds_write_b32 v2, v6
.LBB0_942:
	s_or_b64 exec, exec, s[26:27]
	v_add_u32_e32 v2, 0x400, v12
	v_ashrrev_i32_e32 v6, 8, v2
	s_mov_b32 s10, 0xffffc
	v_cmp_gt_i32_e32 vcc, s10, v6
	v_add_u32_e32 v8, 4, v6
	v_mov_b64_e32 v[6:7], s[2:3]
	v_mad_i64_i32 v[6:7], s[26:27], v8, s12, v[6:7]
	s_mov_b64 s[26:27], 0x480
	s_nop 0
	v_cmp_gt_i64_e64 s[40:41], s[26:27], v[6:7]
	s_and_b64 s[30:31], vcc, s[40:41]
	s_and_saveexec_b64 s[26:27], s[30:31]
	s_cbranch_execz .LBB0_944
	v_ashrrev_i32_e32 v7, 31, v6
	v_lshrrev_b32_e32 v7, 29, v7
	v_add_u32_e32 v7, v6, v7
	v_ashrrev_i32_e32 v8, 3, v7
	v_and_b32_e32 v7, -8, v7
	v_sub_u32_e32 v6, v6, v7
	v_cmp_gt_i32_e32 vcc, 0, v6
	s_mov_b32 s10, 0x38e38e39
	v_lshl_add_u32 v2, v2, 2, 0
	v_cndmask_b32_e32 v7, v215, v216, vcc
	v_mul_lo_u32 v6, v6, v7
	v_add_u32_e32 v6, v6, v8
	v_mul_hi_i32 v7, v6, s10
	v_lshrrev_b32_e32 v8, 31, v7
	v_ashrrev_i32_e32 v7, 6, v7
	v_add_u32_e32 v7, v7, v8
	v_lshlrev_b32_e32 v8, 3, v7
	v_mul_i32_i24_e32 v7, 0x120, v7
	v_sub_u32_e32 v9, 32, v8
	v_sub_u32_e32 v6, v6, v7
	v_min_i32_e32 v9, 8, v9
	v_sub_u32_e32 v10, 0, v6
	v_ashrrev_i32_e32 v7, 31, v6
	v_max_i32_e32 v6, v6, v10
	v_sub_u32_e32 v10, 0, v9
	v_max_i32_e32 v9, v9, v10
	v_cvt_f32_u32_e32 v10, v9
	v_sub_u32_e32 v11, 0, v9
	v_add_u32_e32 v2, 0x20000, v2
	v_rcp_iflag_f32_e32 v10, v10
	s_nop 0
	v_mul_f32_e32 v10, 0x4f7ffffe, v10
	v_cvt_u32_f32_e32 v10, v10
	v_mul_lo_u32 v11, v11, v10
	v_mul_hi_u32 v11, v10, v11
	v_add_u32_e32 v10, v10, v11
	v_mul_hi_u32 v10, v6, v10
	v_mul_lo_u32 v10, v10, v9
	v_sub_u32_e32 v6, v6, v10
	v_cmp_ge_u32_e32 vcc, v6, v9
	v_sub_u32_e32 v10, v6, v9
	s_nop 0
	v_cndmask_b32_e32 v6, v6, v10, vcc
	v_cmp_ge_u32_e32 vcc, v6, v9
	v_sub_u32_e32 v9, v6, v9
	s_nop 0
	v_cndmask_b32_e32 v6, v6, v9, vcc
	v_xor_b32_e32 v6, v6, v7
	v_sub_u32_e32 v6, v6, v7
	v_add_lshl_u32 v6, v8, v6, 8
	v_ashrrev_i32_e32 v7, 31, v6
	v_lshl_add_u64 v[4:5], v[6:7], 2, v[4:5]
	global_load_dword v100, v[4:5], off
	v_add_co_u32_e32 v110, vcc, 0x8000, v4
	s_nop 1
	v_addc_co_u32_e32 v111, vcc, 0, v5, vcc
	global_load_dword v101, v[110:111], off
	v_add_co_u32_e32 v110, vcc, 0x10000, v4
	s_nop 1
	v_addc_co_u32_e32 v111, vcc, 0, v5, vcc
	global_load_dword v102, v[110:111], off
	v_add_co_u32_e32 v110, vcc, 0x18000, v4
	s_nop 1
	v_addc_co_u32_e32 v111, vcc, 0, v5, vcc
	global_load_dword v103, v[110:111], off
	v_add_co_u32_e32 v110, vcc, 0x20000, v4
	s_nop 1
	v_addc_co_u32_e32 v111, vcc, 0, v5, vcc
	global_load_dword v104, v[110:111], off
	v_add_co_u32_e32 v110, vcc, 0x28000, v4
	s_nop 1
	v_addc_co_u32_e32 v111, vcc, 0, v5, vcc
	global_load_dword v105, v[110:111], off
	v_add_co_u32_e32 v110, vcc, 0x30000, v4
	s_nop 1
	v_addc_co_u32_e32 v111, vcc, 0, v5, vcc
	global_load_dword v106, v[110:111], off
	v_add_co_u32_e32 v110, vcc, 0x38000, v4
	s_nop 1
	v_addc_co_u32_e32 v111, vcc, 0, v5, vcc
	global_load_dword v107, v[110:111], off
	s_waitcnt vmcnt(0)
	v_add_f32_e32 v4, 0, v100
	v_add_f32_e32 v4, v4, v101
	v_add_f32_e32 v4, v4, v102
	v_add_f32_e32 v4, v4, v103
	v_add_f32_e32 v4, v4, v104
	v_add_f32_e32 v4, v4, v105
	v_add_f32_e32 v4, v4, v106
	v_add_f32_e32 v4, v4, v107
	v_fmamk_f32 v4, v4, 0x3a000000, v212
	v_rsq_f32_e32 v4, v4
	ds_write_b32 v2, v4

;     __device__ __forceinline__ bool next(int i, Unit& u) const {
;         if (i + i0 >= i1) return false;
;         const long L = (long)(i + i0) * G + c; if (L >= nwg) return false;
;         int wgid = (int)L; { const int q = nwg / NXCD, r = nwg % NXCD, xcd = wgid % NXCD, off = wgid / NXCD; wgid = (xcd < r ? xcd * (q + 1) : r * (q + 1) + (xcd - r) * q) + off; }
;         const int nig = WGM * nN, gid = wgid / nig, fm = gid * WGM, gsz = (nM - fm) < WGM ? (nM - fm) : WGM;
;         u.pm = fm + ((wgid % nig) % gsz); u.pn = (wgid % nig) / gsz;
;         u.aoff = (long)u.pm * a_pm + (long)(u.pn >> a_sh) * a_pn; u.boff = (long)(u.pm >> b_sh) * b_pm + (long)u.pn * b_pn;
; template <class Epi, bool ALIGN_EPI = true>
; __device__ __forceinline__ void gemm_phase(LAS unsigned char* lds, const Gemm g, const Sched& S, const Epi& E) {
;     ...
;         for (int k = 0; k < RSTD_UNITS * 256 / 512; ++k) { const int idx = tid + 512 * k; Unit uu;
;             if (S.next(idx >> 8, uu)) { const float* sp = E.SS + uu.pm * BM + (idx & 255); float ssum = 0.f;
; #pragma unroll
;                 for (int j = 0; j < 8; ++j) ssum += sp[(size_t)j * MROWS];
;                 T[idx] = __builtin_amdgcn_rsqf(ssum * (1.0f / DM) + EPS); } }
.LBB0_2005:
	s_andn2_b64 vcc, exec, s[0:1]
	s_cbranch_vccnz .LBB0_2272
	v_readlane_b32 s6, v244, 40
	s_mov_b64 s[0:1], 0x26000000
	s_mov_b64 s[14:15], 0x3a000000
	s_mov_b64 s[4:5], 0x120000
	s_waitcnt vmcnt(0)
	v_mov_b32_e32 v12, v0
	v_readlane_b32 s7, v244, 41
	s_movk_i32 s16, 0x800
	v_readfirstlane_b32 s18, v12
	s_andn2_b64 vcc, exec, s[6:7]
	s_cbranch_vccnz .LBB0_2031
	s_add_u32 s4, s54, s4
	s_addc_u32 s5, s55, s5
	v_lshlrev_b32_sdwa v2, v214, v12 dst_sel:DWORD dst_unused:UNUSED_PAD src0_sel:DWORD src1_sel:BYTE_0
	s_waitcnt lgkmcnt(0)
	v_lshl_add_u64 v[4:5], s[4:5], 0, v[2:3]
	v_ashrrev_i32_e32 v2, 8, v12
	s_mov_b32 s4, 0x100000
	v_mov_b64_e32 v[6:7], s[2:3]
	v_cmp_gt_i32_e32 vcc, s4, v2
	v_mad_i64_i32 v[6:7], s[4:5], v2, s12, v[6:7]
	s_mov_b64 s[4:5], 0x580
	s_nop 0
	v_cmp_gt_i64_e64 s[40:41], s[4:5], v[6:7]
	s_and_b64 s[6:7], vcc, s[40:41]
	s_and_saveexec_b64 s[4:5], s[6:7]
	s_cbranch_execz .LBB0_2009
	v_ashrrev_i32_e32 v2, 31, v6
	v_lshrrev_b32_e32 v2, 29, v2
	v_add_u32_e32 v2, v6, v2
	v_ashrrev_i32_e32 v7, 3, v2
	v_and_b32_e32 v2, -8, v2
	v_sub_u32_e32 v2, v6, v2
	v_cmp_gt_i32_e32 vcc, 0, v2
	s_mov_b32 s6, 0x2e8ba2e9
	s_nop 0
	v_cndmask_b32_e32 v6, v221, v222, vcc
	v_mul_lo_u32 v2, v2, v6
	v_add_u32_e32 v2, v2, v7
	v_mul_hi_i32 v6, v2, s6
	v_lshrrev_b32_e32 v7, 31, v6
	v_ashrrev_i32_e32 v6, 6, v6
	v_add_u32_e32 v6, v6, v7
	v_lshlrev_b32_e32 v7, 3, v6
	v_mul_i32_i24_e32 v6, 0x160, v6
	v_sub_u32_e32 v8, 32, v7
	v_sub_u32_e32 v2, v2, v6
	v_min_i32_e32 v8, 8, v8
	v_sub_u32_e32 v9, 0, v2
	v_ashrrev_i32_e32 v6, 31, v2
	v_max_i32_e32 v2, v2, v9
	v_sub_u32_e32 v9, 0, v8
	v_max_i32_e32 v8, v8, v9
	v_cvt_f32_u32_e32 v9, v8
	v_sub_u32_e32 v10, 0, v8
	s_mov_b32 s6, 0x10000
	v_rcp_iflag_f32_e32 v9, v9
	s_nop 0
	v_mul_f32_e32 v9, 0x4f7ffffe, v9
	v_cvt_u32_f32_e32 v9, v9
	v_mul_lo_u32 v10, v10, v9
	v_mul_hi_u32 v10, v9, v10
	v_add_u32_e32 v9, v9, v10
	v_mul_hi_u32 v9, v2, v9
	v_mul_lo_u32 v9, v9, v8
	v_sub_u32_e32 v2, v2, v9
	v_cmp_ge_u32_e32 vcc, v2, v8
	v_sub_u32_e32 v9, v2, v8
	s_nop 0
	v_cndmask_b32_e32 v2, v2, v9, vcc
	v_cmp_ge_u32_e32 vcc, v2, v8
	v_sub_u32_e32 v8, v2, v8
	s_nop 0
	v_cndmask_b32_e32 v2, v2, v8, vcc
	v_xor_b32_e32 v2, v2, v6
	v_sub_u32_e32 v2, v2, v6
	v_add_lshl_u32 v6, v7, v2, 8
	v_ashrrev_i32_e32 v7, 31, v6
	v_lshl_add_u64 v[6:7], v[6:7], 2, v[4:5]
	global_load_dword v100, v[6:7], off
	v_add_co_u32_e32 v110, vcc, 0x8000, v6
	s_nop 1
	v_addc_co_u32_e32 v111, vcc, 0, v7, vcc
	global_load_dword v101, v[110:111], off
	v_add_co_u32_e32 v110, vcc, 0x10000, v6
	s_nop 1
	v_addc_co_u32_e32 v111, vcc, 0, v7, vcc
	global_load_dword v102, v[110:111], off
	v_add_co_u32_e32 v110, vcc, 0x18000, v6
	s_nop 1
	v_addc_co_u32_e32 v111, vcc, 0, v7, vcc
	global_load_dword v103, v[110:111], off
	v_add_co_u32_e32 v110, vcc, 0x20000, v6
	s_nop 1
	v_addc_co_u32_e32 v111, vcc, 0, v7, vcc
	global_load_dword v104, v[110:111], off
	v_add_co_u32_e32 v110, vcc, 0x28000, v6
	s_nop 1
	v_addc_co_u32_e32 v111, vcc, 0, v7, vcc
	global_load_dword v105, v[110:111], off
	v_add_co_u32_e32 v110, vcc, 0x30000, v6
	s_nop 1
	v_addc_co_u32_e32 v111, vcc, 0, v7, vcc
	global_load_dword v106, v[110:111], off
	v_add_co_u32_e32 v110, vcc, 0x38000, v6
	s_nop 1
	v_addc_co_u32_e32 v111, vcc, 0, v7, vcc
	global_load_dword v107, v[110:111], off
	s_mov_b32 s6, 0x28000
	s_waitcnt vmcnt(0)
	v_add_f32_e32 v2, 0, v100
	v_add_f32_e32 v2, v2, v101
	v_add_f32_e32 v2, v2, v102
	v_add_f32_e32 v2, v2, v103
	v_add_f32_e32 v2, v2, v104
	v_add_f32_e32 v2, v2, v105
	v_add_f32_e32 v2, v2, v106
	v_add_f32_e32 v2, v2, v107
	v_fmamk_f32 v2, v2, 0x3a000000, v212
	v_rsq_f32_e32 v2, v2
	v_lshl_add_u32 v6, v12, 2, 0
	v_add_u32_e32 v6, 0x20000, v6
	ds_write_b32 v6, v2
;     __device__ __forceinline__ bool next(int i, Unit& u) const {
;         if (i + i0 >= i1) return false;
;         const long L = (long)(i + i0) * G + c; if (L >= nwg) return false;
;         int wgid = (int)L; { const int q = nwg / NXCD, r = nwg % NXCD, xcd = wgid % NXCD, off = wgid / NXCD; wgid = (xcd < r ? xcd * (q + 1) : r * (q + 1) + (xcd - r) * q) + off; }
;         const int nig = WGM * nN, gid = wgid / nig, fm = gid * WGM, gsz = (nM - fm) < WGM ? (nM - fm) : WGM;
;         u.pm = fm + ((wgid % nig) % gsz); u.pn = (wgid % nig) / gsz;
;         u.aoff = (long)u.pm * a_pm + (long)(u.pn >> a_sh) * a_pn; u.boff = (long)(u.pm >> b_sh) * b_pm + (long)u.pn * b_pn;
; template <class Epi, bool ALIGN_EPI = true>
; __device__ __forceinline__ void gemm_phase(LAS unsigned char* lds, const Gemm g, const Sched& S, const Epi& E) {
;     ...
;         for (int k = 0; k < RSTD_UNITS * 256 / 512; ++k) { const int idx = tid + 512 * k; Unit uu;
;             if (S.next(idx >> 8, uu)) { const float* sp = E.SS + uu.pm * BM + (idx & 255); float ssum = 0.f;
; #pragma unroll
;                 for (int j = 0; j < 8; ++j) ssum += sp[(size_t)j * MROWS];
;                 T[idx] = __builtin_amdgcn_rsqf(ssum * (1.0f / DM) + EPS); } }
.LBB0_2009:
	s_or_b64 exec, exec, s[4:5]
	v_add_u32_e32 v2, 0x200, v12
	v_ashrrev_i32_e32 v8, 8, v2
	s_mov_b32 s4, 0x100000
	v_mov_b64_e32 v[6:7], s[2:3]
	v_cmp_gt_i32_e32 vcc, s4, v8
	v_mad_i64_i32 v[6:7], s[4:5], v8, s12, v[6:7]
	s_mov_b64 s[4:5], 0x580
	s_nop 0
	v_cmp_gt_i64_e64 s[40:41], s[4:5], v[6:7]
	s_and_b64 s[6:7], vcc, s[40:41]
	s_and_saveexec_b64 s[4:5], s[6:7]
	s_cbranch_execz .LBB0_2011
	v_ashrrev_i32_e32 v7, 31, v6
	v_lshrrev_b32_e32 v7, 29, v7
	v_add_u32_e32 v7, v6, v7
	v_ashrrev_i32_e32 v8, 3, v7
	v_and_b32_e32 v7, -8, v7
	v_sub_u32_e32 v6, v6, v7
	v_cmp_gt_i32_e32 vcc, 0, v6
	s_mov_b32 s6, 0x2e8ba2e9
	v_lshl_add_u32 v2, v2, 2, 0
	v_cndmask_b32_e32 v7, v221, v222, vcc
	v_mul_lo_u32 v6, v6, v7
	v_add_u32_e32 v6, v6, v8
	v_mul_hi_i32 v7, v6, s6
	v_lshrrev_b32_e32 v8, 31, v7
	v_ashrrev_i32_e32 v7, 6, v7
	v_add_u32_e32 v7, v7, v8
	v_lshlrev_b32_e32 v8, 3, v7
	v_mul_i32_i24_e32 v7, 0x160, v7
	v_sub_u32_e32 v9, 32, v8
	v_sub_u32_e32 v6, v6, v7
	v_min_i32_e32 v9, 8, v9
	v_sub_u32_e32 v10, 0, v6
	v_ashrrev_i32_e32 v7, 31, v6
	v_max_i32_e32 v6, v6, v10
	v_sub_u32_e32 v10, 0, v9
	v_max_i32_e32 v9, v9, v10
	v_cvt_f32_u32_e32 v10, v9
	v_sub_u32_e32 v11, 0, v9
	s_mov_b32 s6, 0x10000
	v_add_u32_e32 v2, 0x20000, v2
	v_rcp_iflag_f32_e32 v10, v10
	s_nop 0
	v_mul_f32_e32 v10, 0x4f7ffffe, v10
	v_cvt_u32_f32_e32 v10, v10
	v_mul_lo_u32 v11, v11, v10
	v_mul_hi_u32 v11, v10, v11
	v_add_u32_e32 v10, v10, v11
	v_mul_hi_u32 v10, v6, v10
	v_mul_lo_u32 v10, v10, v9
	v_sub_u32_e32 v6, v6, v10
	v_cmp_ge_u32_e32 vcc, v6, v9
	v_sub_u32_e32 v10, v6, v9
	s_nop 0
	v_cndmask_b32_e32 v6, v6, v10, vcc
	v_cmp_ge_u32_e32 vcc, v6, v9
	v_sub_u32_e32 v9, v6, v9
	s_nop 0
	v_cndmask_b32_e32 v6, v6, v9, vcc
	v_xor_b32_e32 v6, v6, v7
	v_sub_u32_e32 v6, v6, v7
	v_add_lshl_u32 v6, v8, v6, 8
	v_ashrrev_i32_e32 v7, 31, v6
	v_lshl_add_u64 v[6:7], v[6:7], 2, v[4:5]
	global_load_dword v100, v[6:7], off
	v_add_co_u32_e32 v110, vcc, 0x8000, v6
	s_nop 1
	v_addc_co_u32_e32 v111, vcc, 0, v7, vcc
	global_load_dword v101, v[110:111], off
	v_add_co_u32_e32 v110, vcc, 0x10000, v6
	s_nop 1
	v_addc_co_u32_e32 v111, vcc, 0, v7, vcc
	global_load_dword v102, v[110:111], off
	v_add_co_u32_e32 v110, vcc, 0x18000, v6
	s_nop 1
	v_addc_co_u32_e32 v111, vcc, 0, v7, vcc
	global_load_dword v103, v[110:111], off
	v_add_co_u32_e32 v110, vcc, 0x20000, v6
	s_nop 1
	v_addc_co_u32_e32 v111, vcc, 0, v7, vcc
	global_load_dword v104, v[110:111], off
	v_add_co_u32_e32 v110, vcc, 0x28000, v6
	s_nop 1
	v_addc_co_u32_e32 v111, vcc, 0, v7, vcc
	global_load_dword v105, v[110:111], off
	v_add_co_u32_e32 v110, vcc, 0x30000, v6
	s_nop 1
	v_addc_co_u32_e32 v111, vcc, 0, v7, vcc
	global_load_dword v106, v[110:111], off
	v_add_co_u32_e32 v110, vcc, 0x38000, v6
	s_nop 1
	v_addc_co_u32_e32 v111, vcc, 0, v7, vcc
	global_load_dword v107, v[110:111], off
	s_mov_b32 s6, 0x28000
	s_waitcnt vmcnt(0)
	v_add_f32_e32 v6, 0, v100
	v_add_f32_e32 v6, v6, v101
	v_add_f32_e32 v6, v6, v102
	v_add_f32_e32 v6, v6, v103
	v_add_f32_e32 v6, v6, v104
	v_add_f32_e32 v6, v6, v105
	v_add_f32_e32 v6, v6, v106
	v_add_f32_e32 v6, v6, v107
	v_fmamk_f32 v6, v6, 0x3a000000, v212
	v_rsq_f32_e32 v6, v6
	ds_write_b32 v2, v6
.LBB0_2011:
	s_or_b64 exec, exec, s[4:5]
	v_add_u32_e32 v2, 0x400, v12
	v_ashrrev_i32_e32 v8, 8, v2
	s_mov_b32 s4, 0x100000
	v_mov_b64_e32 v[6:7], s[2:3]
	v_cmp_gt_i32_e32 vcc, s4, v8
	v_mad_i64_i32 v[6:7], s[4:5], v8, s12, v[6:7]
	s_mov_b64 s[4:5], 0x580
	s_nop 0
	v_cmp_gt_i64_e64 s[40:41], s[4:5], v[6:7]
	s_and_b64 s[6:7], vcc, s[40:41]
	s_and_saveexec_b64 s[4:5], s[6:7]
	s_cbranch_execz .LBB0_2013
	v_ashrrev_i32_e32 v7, 31, v6
	v_lshrrev_b32_e32 v7, 29, v7
	v_add_u32_e32 v7, v6, v7
	v_ashrrev_i32_e32 v8, 3, v7
	v_and_b32_e32 v7, -8, v7
	v_sub_u32_e32 v6, v6, v7
	v_cmp_gt_i32_e32 vcc, 0, v6
	s_mov_b32 s6, 0x2e8ba2e9
	v_lshl_add_u32 v2, v2, 2, 0
	v_cndmask_b32_e32 v7, v221, v222, vcc
	v_mul_lo_u32 v6, v6, v7
	v_add_u32_e32 v6, v6, v8
	v_mul_hi_i32 v7, v6, s6
	v_lshrrev_b32_e32 v8, 31, v7
	v_ashrrev_i32_e32 v7, 6, v7
	v_add_u32_e32 v7, v7, v8
	v_lshlrev_b32_e32 v8, 3, v7
	v_mul_i32_i24_e32 v7, 0x160, v7
	v_sub_u32_e32 v9, 32, v8
	v_sub_u32_e32 v6, v6, v7
	v_min_i32_e32 v9, 8, v9
	v_sub_u32_e32 v10, 0, v6
	v_ashrrev_i32_e32 v7, 31, v6
	v_max_i32_e32 v6, v6, v10
	v_sub_u32_e32 v10, 0, v9
	v_max_i32_e32 v9, v9, v10
	v_cvt_f32_u32_e32 v10, v9
	v_sub_u32_e32 v11, 0, v9
	s_mov_b32 s6, 0x10000
	v_add_u32_e32 v2, 0x20000, v2
	v_rcp_iflag_f32_e32 v10, v10
	s_nop 0
	v_mul_f32_e32 v10, 0x4f7ffffe, v10
	v_cvt_u32_f32_e32 v10, v10
	v_mul_lo_u32 v11, v11, v10
	v_mul_hi_u32 v11, v10, v11
	v_add_u32_e32 v10, v10, v11
	v_mul_hi_u32 v10, v6, v10
	v_mul_lo_u32 v10, v10, v9
	v_sub_u32_e32 v6, v6, v10
	v_cmp_ge_u32_e32 vcc, v6, v9
	v_sub_u32_e32 v10, v6, v9
	s_nop 0
	v_cndmask_b32_e32 v6, v6, v10, vcc
	v_cmp_ge_u32_e32 vcc, v6, v9
	v_sub_u32_e32 v9, v6, v9
	s_nop 0
	v_cndmask_b32_e32 v6, v6, v9, vcc
	v_xor_b32_e32 v6, v6, v7
	v_sub_u32_e32 v6, v6, v7
	v_add_lshl_u32 v6, v8, v6, 8
	v_ashrrev_i32_e32 v7, 31, v6
	v_lshl_add_u64 v[4:5], v[6:7], 2, v[4:5]
	global_load_dword v100, v[4:5], off
	v_add_co_u32_e32 v110, vcc, 0x8000, v4
	s_nop 1
	v_addc_co_u32_e32 v111, vcc, 0, v5, vcc
	global_load_dword v101, v[110:111], off
	v_add_co_u32_e32 v110, vcc, 0x10000, v4
	s_nop 1
	v_addc_co_u32_e32 v111, vcc, 0, v5, vcc
	global_load_dword v102, v[110:111], off
	v_add_co_u32_e32 v110, vcc, 0x18000, v4
	s_nop 1
	v_addc_co_u32_e32 v111, vcc, 0, v5, vcc
	global_load_dword v103, v[110:111], off
	v_add_co_u32_e32 v110, vcc, 0x20000, v4
	s_nop 1
	v_addc_co_u32_e32 v111, vcc, 0, v5, vcc
	global_load_dword v104, v[110:111], off
	v_add_co_u32_e32 v110, vcc, 0x28000, v4
	s_nop 1
	v_addc_co_u32_e32 v111, vcc, 0, v5, vcc
	global_load_dword v105, v[110:111], off
	v_add_co_u32_e32 v110, vcc, 0x30000, v4
	s_nop 1
	v_addc_co_u32_e32 v111, vcc, 0, v5, vcc
	global_load_dword v106, v[110:111], off
	v_add_co_u32_e32 v110, vcc, 0x38000, v4
	s_nop 1
	v_addc_co_u32_e32 v111, vcc, 0, v5, vcc
	global_load_dword v107, v[110:111], off
	s_mov_b32 s6, 0x28000
	s_waitcnt vmcnt(0)
	v_add_f32_e32 v4, 0, v100
	v_add_f32_e32 v4, v4, v101
	v_add_f32_e32 v4, v4, v102
	v_add_f32_e32 v4, v4, v103
	v_add_f32_e32 v4, v4, v104
	v_add_f32_e32 v4, v4, v105
	v_add_f32_e32 v4, v4, v106
	v_add_f32_e32 v4, v4, v107
	v_fmamk_f32 v4, v4, 0x3a000000, v212
	v_rsq_f32_e32 v4, v4
	ds_write_b32 v2, v4
